# end of layer-0 out-proj phase: each workgroup touches every line of its share of x so the next row-update phase reads x from the memory-side cache
# baseline (speedup 1.0000x reference)
.LBB0_705:
	v_readlane_b32 s0, v255, 19
	v_readlane_b32 s40, v252, 11
	s_waitcnt lgkmcnt(0)
	s_add_i32 s5, s0, 1
	s_cmp_lg_u32 s0, 6
	s_cbranch_scc1 .Lwarm_skip
	v_readlane_b32 s42, v252, 20
	v_readlane_b32 s43, v252, 21
	v_readlane_b32 s44, v252, 0
	s_sub_u32 s42, s42, 0x1c0
	s_subb_u32 s43, s43, 0
	s_load_dwordx2 s[42:43], s[42:43], 0x0
	s_lshl_b32 s44, s44, 17
	v_lshlrev_b32_e32 v60, 7, v220
	v_add_u32_e32 v60, s44, v60
	s_waitcnt lgkmcnt(0)
	s_nop 0
	global_load_dword v61, v60, s[42:43]
	v_add_u32_e32 v62, 0x8000, v60
	global_load_dword v63, v62, s[42:43]
	v_add_u32_e32 v60, 0x10000, v60
	global_load_dword v61, v60, s[42:43]
	v_add_u32_e32 v62, 0x10000, v62
	global_load_dword v63, v62, s[42:43]
	s_waitcnt vmcnt(0)
.Lwarm_skip:
	v_readlane_b32 s45, v252, 16
	s_cmp_ge_i32 s5, s45
	s_mov_b64 s[0:1], -1
	v_readlane_b32 s41, v252, 12
	v_readlane_b32 s42, v252, 13
	v_readlane_b32 s43, v252, 14
	v_readlane_b32 s44, v252, 15
	v_readlane_b32 s46, v252, 17
	v_readlane_b32 s47, v252, 18
	s_cbranch_scc1 .LBB0_8
	v_readlane_b32 s40, v252, 11
	v_readlane_b32 s46, v252, 17
	s_cmp_lt_i32 s46, 2
	v_readlane_b32 s41, v252, 12
	v_readlane_b32 s42, v252, 13
	v_readlane_b32 s43, v252, 14
	v_readlane_b32 s44, v252, 15
	v_readlane_b32 s45, v252, 16
	v_readlane_b32 s47, v252, 18
	s_cbranch_scc1 .LBB0_713
	s_cmp_gt_i32 s46, 2
	s_cbranch_scc0 .LBB0_726
	s_mov_b64 s[0:1], 0
	s_cmp_eq_u32 s46, 3
	s_mov_b64 s[28:29], 0
	s_cbranch_scc0 .LBB0_727
	s_waitcnt vmcnt(0)
	s_waitcnt vmcnt(63) expcnt(7) lgkmcnt(15)
	s_barrier
	s_mov_b64 s[28:29], exec
	v_readlane_b32 s2, v252, 9
	v_readlane_b32 s3, v252, 10
	s_and_b64 s[2:3], s[28:29], s[2:3]
	s_mov_b64 exec, s[2:3]
	s_cbranch_execz .LBB0_753
	s_mov_b64 s[2:3], exec
	buffer_wbl2 sc1
	s_waitcnt vmcnt(0)
	s_waitcnt vmcnt(0)
	v_mbcnt_lo_u32_b32 v0, s2, 0
	v_mbcnt_hi_u32_b32 v0, s3, v0
	v_cmp_eq_u32_e32 vcc, 0, v0
	s_and_saveexec_b64 s[38:39], vcc
	s_cbranch_execz .LBB0_712
	s_bcnt1_i32_b64 s2, s[2:3]
	v_readlane_b32 s40, v252, 11
	v_mov_b32_e32 v0, s2
	v_readlane_b32 s42, v252, 13
	v_readlane_b32 s43, v252, 14
	v_readlane_b32 s41, v252, 12
	v_readlane_b32 s44, v252, 15
	v_readlane_b32 s45, v252, 16
	v_readlane_b32 s46, v252, 17
	v_readlane_b32 s47, v252, 18
	global_atomic_add v193, v0, s[42:43] offset:128
